# P2: static s_setprio 1 for waves 4-7 during the FoX / retention-KV queue phase
# baseline (speedup 1.0000x reference)
.LBB0_439:
	s_cmp_lt_i32 s92, 3
	s_cselect_b64 s[0:1], -1, 0
	s_and_b64 s[4:5], s[0:1], s[4:5]
	v_bfe_u32 v133, v223, 5, 1
	s_andn2_b64 vcc, exec, s[4:5]
	v_and_b32_e32 v177, 16, v223
	v_and_b32_e32 v176, 31, v223
	v_lshlrev_b32_e32 v180, 4, v133
	v_lshlrev_b32_e32 v178, 2, v133
	s_cbranch_vccnz .LBB0_483
	v_readlane_b32 s4, v252, 8
	s_waitcnt vmcnt(0)
	v_lshlrev_b32_e32 v0, 2, v224
	v_readlane_b32 s16, v252, 20
	v_readlane_b32 s17, v252, 21
	v_readlane_b32 s18, v252, 22
	v_readlane_b32 s19, v252, 23
	s_nop 2
	global_load_dword v3, v0, s[16:17]
	s_nop 0
	global_load_dword v4, v0, s[18:19]
	v_mbcnt_lo_u32_b32 v2, -1, 0
	v_lshrrev_b32_e32 v135, 8, v223
	v_lshrrev_b32_e32 v5, 2, v223
	v_bfe_u32 v146, v223, 2, 6
	v_lshlrev_b32_e32 v6, 4, v223
	v_mul_u32_u24_e32 v10, 0x90, v176
	v_mbcnt_hi_u32_b32 v11, -1, v2
	v_and_b32_e32 v2, 48, v6
	v_bitop3_b32 v5, v5, 63, v5 bitop3:0xc
	v_mul_u32_u24_e32 v6, 0x4800, v135
	v_mul_u32_u24_e32 v12, 0x90, v146
	v_add3_u32 v152, 0, v180, v10
	v_and_b32_e32 v10, 64, v11
	v_xor_b32_e32 v15, 1, v11
	v_cvt_f32_ubyte0_e32 v153, v5
	v_add3_u32 v5, 0, v6, v12
	v_lshlrev_b32_e32 v6, 1, v2
	v_lshlrev_b32_e32 v136, 1, v2
	v_add_u32_e32 v2, 64, v10
	v_readlane_b32 s8, v252, 12
	v_bfe_u32 v7, v223, 2, 2
	v_cmp_lt_i32_e32 vcc, v15, v2
	v_readlane_b32 s6, v252, 10
	v_readlane_b32 s9, v252, 13
	s_add_u32 s8, s30, 0x3800
	v_lshl_or_b32 v13, v133, 3, v7
	v_or_b32_e32 v7, v178, v7
	v_add_u32_e32 v160, v5, v6
	v_cndmask_b32_e32 v5, v11, v15, vcc
	v_lshlrev_b32_e32 v8, 2, v223
	s_addc_u32 s9, s31, 0
	s_add_i32 s6, 0, 0x12000
	v_mul_u32_u24_e32 v159, 0x90, v7
	v_lshlrev_b32_e32 v5, 2, v5
	v_and_or_b32 v151, v8, 12, v177
	v_add_u32_e32 v156, s6, v8
	v_xor_b32_e32 v16, 2, v11
	v_cmp_lt_i32_e32 vcc, v16, v2
	v_xor_b32_e32 v17, 4, v11
	v_xor_b32_e32 v18, 8, v11
	v_cndmask_b32_e32 v6, v11, v16, vcc
	v_lshlrev_b32_e32 v6, 2, v6
	v_cmp_lt_i32_e32 vcc, v17, v2
	v_xor_b32_e32 v19, 16, v11
	v_xor_b32_e32 v20, 32, v11
	s_add_u32 s50, s30, 0xd000000
	v_lshrrev_b32_e32 v132, 3, v223
	v_and_b32_e32 v9, 7, v223
	s_addc_u32 s51, s31, 0
	v_readlane_b32 s5, v252, 9
	v_readlane_b32 s7, v252, 11
	v_readlane_b32 s10, v252, 14
	v_readlane_b32 s11, v252, 15
	v_readlane_b32 s12, v252, 16
	v_readlane_b32 s13, v252, 17
	v_lshlrev_b32_e32 v0, 3, v133
	v_mov_b32_e32 v147, 0x7f
	s_movk_i32 s4, 0x80
	v_lshlrev_b32_e32 v134, 3, v9
	v_mul_u32_u24_e32 v14, 0x90, v132
	v_lshlrev_b32_e32 v9, 4, v9
	s_add_u32 s52, s30, 0x2780000
	s_mov_b32 s7, 0
	v_mov_b32_e32 v1, 0
	v_lshl_or_b32 v148, v133, 8, v176
	v_add_u32_e32 v149, 0xf00, v223
	s_movk_i32 s3, 0x5ff
	s_mov_b32 s27, 0xc2fc0000
	s_mov_b32 s35, 0x800000
	s_movk_i32 s48, 0x1000
	s_movk_i32 s49, 0x1c00
	v_lshl_or_b32 v150, v224, 7, v147
	v_cmp_gt_u32_e64 s[4:5], s4, v223
	v_mul_u32_u24_e32 v154, 0x90, v13
	v_add3_u32 v155, 0, v14, v9
	v_add_u32_e32 v157, s6, v180
	v_lshlrev_b32_e32 v158, 1, v151
	s_addc_u32 s53, s31, 0
	s_waitcnt vmcnt(1)
	v_and_b32_e32 v7, 0x7fffffff, v3
	s_waitcnt vmcnt(0)
	v_and_b32_e32 v8, 0x7fffffff, v4
	ds_bpermute_b32 v7, v5, v7
	ds_bpermute_b32 v5, v5, v8
	v_max_f32_e64 v3, |v3|, |v3|
	v_max_f32_e64 v4, |v4|, |v4|
	s_add_i32 s54, 0, 0x23f80
	s_waitcnt lgkmcnt(1)
	v_max_f32_e32 v7, v7, v7
	s_waitcnt lgkmcnt(0)
	v_max_f32_e32 v5, v5, v5
	v_max_f32_e32 v3, v3, v7
	v_max_f32_e32 v4, v4, v5
	ds_bpermute_b32 v5, v6, v3
	ds_bpermute_b32 v6, v6, v4
	v_cndmask_b32_e32 v7, v11, v17, vcc
	v_lshlrev_b32_e32 v7, 2, v7
	v_cmp_lt_i32_e32 vcc, v18, v2
	s_waitcnt lgkmcnt(1)
	v_max_f32_e32 v5, v5, v5
	s_waitcnt lgkmcnt(0)
	v_max_f32_e32 v6, v6, v6
	v_max_f32_e32 v3, v3, v5
	v_max_f32_e32 v4, v4, v6
	ds_bpermute_b32 v5, v7, v3
	ds_bpermute_b32 v6, v7, v4
	v_cndmask_b32_e32 v7, v11, v18, vcc
	v_lshlrev_b32_e32 v7, 2, v7
	v_cmp_lt_i32_e32 vcc, v19, v2
	s_waitcnt lgkmcnt(1)
	v_max_f32_e32 v5, v5, v5
	s_waitcnt lgkmcnt(0)
	v_max_f32_e32 v6, v6, v6
	v_max_f32_e32 v3, v3, v5
	v_max_f32_e32 v4, v4, v6
	ds_bpermute_b32 v5, v7, v3
	ds_bpermute_b32 v6, v7, v4
	v_cndmask_b32_e32 v7, v11, v19, vcc
	v_lshlrev_b32_e32 v7, 2, v7
	v_cmp_lt_i32_e32 vcc, v20, v2
	s_waitcnt lgkmcnt(1)
	v_max_f32_e32 v5, v5, v5
	s_waitcnt lgkmcnt(0)
	v_max_f32_e32 v6, v6, v6
	v_max_f32_e32 v3, v3, v5
	v_max_f32_e32 v4, v4, v6
	ds_bpermute_b32 v5, v7, v3
	ds_bpermute_b32 v6, v7, v4
	v_cndmask_b32_e32 v2, v11, v20, vcc
	v_lshlrev_b32_e32 v161, 2, v2
	v_lshlrev_b32_e32 v138, 1, v0
	s_waitcnt lgkmcnt(1)
	v_max_f32_e32 v2, v5, v5
	s_waitcnt lgkmcnt(0)
	v_max_f32_e32 v5, v6, v6
	v_max_f32_e32 v2, v3, v2
	v_max_f32_e32 v3, v4, v5
	ds_bpermute_b32 v4, v161, v2
	ds_bpermute_b32 v5, v161, v3
	s_mov_b64 s[10:11], 0x1000
	s_mov_b32 s55, 0x70000
	s_mov_b64 s[12:13], 0x4000400
	s_waitcnt lgkmcnt(1)
	v_max_f32_e32 v4, v4, v4
	s_waitcnt lgkmcnt(0)
	v_max_f32_e32 v5, v5, v5
	v_max_f32_e32 v2, v2, v4
	v_max_f32_e32 v3, v3, v5
	v_mul_f32_e32 v2, 0x41000000, v2
	v_mul_f32_e32 v2, v3, v2
	v_mul_f32_e32 v2, 0x3fb8aa3b, v2
	v_fmaak_f32 v162, 2.0, v2, 0x42200000
	s_brev_b32 s56, 32
	v_mov_b32_e32 v163, 0x42800000
	v_mov_b32_e32 v164, 0x42000000
	v_not_b32_e32 v165, 63
	v_mov_b32_e32 v166, 0x1c00
	v_mov_b32_e32 v167, 0xff800000
	v_readlane_b32 s14, v252, 18
	v_readlane_b32 s15, v252, 19
	v_readfirstlane_b32 s98, v223
	s_nop 3
	s_cmp_lt_u32 s98, 0x100
	s_cbranch_scc1 .Lprio_p2
	s_setprio 1
.Lprio_p2:
	s_branch .LBB0_445
.LBB0_441:
	v_mov_b32_e32 v34, 0
	v_mov_b32_e32 v35, v34
	v_mov_b32_e32 v36, v34
	v_mov_b32_e32 v37, v34
	v_mov_b32_e32 v38, v34
	v_mov_b32_e32 v39, v34
	v_mov_b32_e32 v40, v34
	v_mov_b32_e32 v41, v34
	v_mov_b32_e32 v42, v34
	v_mov_b32_e32 v43, v34
	v_mov_b32_e32 v44, v34
	v_mov_b32_e32 v45, v34
	v_mov_b32_e32 v46, v34
	v_mov_b32_e32 v47, v34
	v_mov_b32_e32 v48, v34
	v_mov_b32_e32 v49, v34
	v_mov_b64_e32 v[18:19], v[34:35]
	v_mov_b64_e32 v[2:3], v[34:35]
	v_mov_b64_e32 v[20:21], v[36:37]
	v_mov_b64_e32 v[22:23], v[38:39]
	v_mov_b64_e32 v[24:25], v[40:41]
	v_mov_b64_e32 v[26:27], v[42:43]
	v_mov_b64_e32 v[28:29], v[44:45]
	v_mov_b64_e32 v[30:31], v[46:47]
	v_mov_b64_e32 v[32:33], v[48:49]
	v_mov_b64_e32 v[4:5], v[36:37]
	v_mov_b64_e32 v[6:7], v[38:39]
	v_mov_b64_e32 v[8:9], v[40:41]
	v_mov_b64_e32 v[10:11], v[42:43]
	v_mov_b64_e32 v[12:13], v[44:45]
	v_mov_b64_e32 v[14:15], v[46:47]
	v_mov_b64_e32 v[16:17], v[48:49]

.LBB0_483:
	s_setprio 0
	s_cmp_gt_i32 s93, 3
	s_cselect_b64 s[4:5], -1, 0
	s_and_b64 s[0:1], s[0:1], s[4:5]
	s_and_b64 s[0:1], s[0:1], s[22:23]
	s_andn2_b64 vcc, exec, s[0:1]
	s_cbranch_vccnz .LBB0_537
	s_waitcnt vmcnt(0)
	s_barrier
	s_and_saveexec_b64 s[0:1], s[90:91]
	s_cbranch_execz .LBB0_536
	s_add_i32 s3, 0, 0x23f20
	s_waitcnt vmcnt(0)
	v_mov_b32_e32 v0, s3
	s_waitcnt vmcnt(0) expcnt(0) lgkmcnt(0)
	ds_read_b32 v2, v0
	s_add_i32 s3, 0, 0x23f24
	v_mov_b32_e32 v0, s3
	ds_read_b32 v0, v0
	s_waitcnt lgkmcnt(1)
	v_cmp_ne_u32_e32 vcc, 0, v2
	s_cbranch_vccnz .LBB0_500
	s_load_dwordx2 s[8:9], s[94:95], 0x4
	s_add_u32 s4, s30, 0x1000
	s_addc_u32 s5, s31, 0
	s_add_u32 s6, s30, 0x1100
	s_addc_u32 s7, s31, 0
	s_waitcnt lgkmcnt(0)
	s_mul_i32 s3, s8, s26
	s_add_u32 s8, s30, 0x1200
	s_mul_i32 s3, s3, s9
	s_addc_u32 s9, s31, 0
	s_add_u32 s10, s30, 0x1300
	s_addc_u32 s11, s31, 0
	s_mov_b32 s18, 1
	v_mov_b32_e32 v16, 0
	s_branch .LBB0_488
